# static priority raise for the LEADING half in the six GEMM K-loops (no toggling)
# baseline (speedup 1.0000x reference)
.LBB0_204:
	s_ashr_i32 s27, s26, 31
	s_lshl_b64 s[16:17], s[26:27], 20
	s_add_u32 s38, s0, s16
	s_addc_u32 s39, s1, s17
	s_and_b64 s[16:17], s[36:37], exec
	s_cselect_b32 s27, s39, s43
	s_cselect_b32 s73, s38, s42
	s_ashr_i32 s23, s22, 31
	s_lshl_b64 s[16:17], s[22:23], 20
	v_readlane_b32 s23, v255, 4
	s_add_u32 s40, s23, s16
	v_readlane_b32 s16, v255, 5
	s_addc_u32 s41, s16, s17
	s_and_b64 s[16:17], s[36:37], exec
	s_cselect_b32 s23, s41, s29
	s_cselect_b32 s74, s40, s28
	s_add_u32 s42, s42, 0x80080
	s_addc_u32 s43, s43, 0
	s_add_u32 s77, s28, 0x100
	v_mov_b32_e32 v4, 0
	s_addc_u32 s78, s29, 0
	s_mov_b32 s88, -2
	v_mov_b32_e32 v5, v4
	v_mov_b32_e32 v6, v4
	v_mov_b32_e32 v7, v4
	v_mov_b32_e32 v8, v4
	v_mov_b32_e32 v9, v4
	v_mov_b32_e32 v10, v4
	v_mov_b32_e32 v11, v4
	v_mov_b32_e32 v20, v4
	v_mov_b32_e32 v21, v4
	s_waitcnt lgkmcnt(0)
	v_mov_b32_e32 v22, v4
	v_mov_b32_e32 v23, v4
	v_mov_b32_e32 v24, v4
	v_mov_b32_e32 v25, v4
	v_mov_b32_e32 v26, v4
	v_mov_b32_e32 v27, v4
	v_mov_b32_e32 v36, v4
	v_mov_b32_e32 v37, v4
	v_mov_b32_e32 v38, v4
	v_mov_b32_e32 v39, v4
	v_mov_b32_e32 v40, v4
	v_mov_b32_e32 v41, v4
	v_mov_b32_e32 v42, v4
	v_mov_b32_e32 v43, v4
	v_mov_b32_e32 v52, v4
	v_mov_b32_e32 v53, v4
	v_mov_b32_e32 v54, v4
	v_mov_b32_e32 v55, v4
	v_mov_b32_e32 v56, v4
	v_mov_b32_e32 v57, v4
	v_mov_b32_e32 v58, v4
	v_mov_b32_e32 v59, v4
	v_mov_b32_e32 v12, v4
	v_mov_b32_e32 v13, v4
	v_mov_b32_e32 v14, v4
	v_mov_b32_e32 v15, v4
	v_mov_b32_e32 v16, v4
	v_mov_b32_e32 v17, v4
	v_mov_b32_e32 v18, v4
	v_mov_b32_e32 v19, v4
	v_mov_b32_e32 v28, v4
	v_mov_b32_e32 v29, v4
	v_mov_b32_e32 v30, v4
	v_mov_b32_e32 v31, v4
	v_mov_b32_e32 v32, v4
	v_mov_b32_e32 v33, v4
	v_mov_b32_e32 v34, v4
	v_mov_b32_e32 v35, v4
	v_mov_b32_e32 v44, v4
	v_mov_b32_e32 v45, v4
	v_mov_b32_e32 v46, v4
	v_mov_b32_e32 v47, v4
	v_mov_b32_e32 v48, v4
	v_mov_b32_e32 v49, v4
	v_mov_b32_e32 v50, v4
	v_mov_b32_e32 v51, v4
	v_mov_b32_e32 v60, v4
	v_mov_b32_e32 v61, v4
	v_mov_b32_e32 v62, v4
	v_mov_b32_e32 v63, v4
	v_mov_b32_e32 v64, v4
	v_mov_b32_e32 v65, v4
	v_mov_b32_e32 v66, v4
	v_mov_b32_e32 v67, v4
	v_mov_b32_e32 v68, v4
	v_mov_b32_e32 v69, v4
	v_mov_b32_e32 v70, v4
	v_mov_b32_e32 v71, v4
	v_mov_b32_e32 v72, v4
	v_mov_b32_e32 v73, v4
	v_mov_b32_e32 v74, v4
	v_mov_b32_e32 v75, v4
	v_mov_b32_e32 v84, v4
	v_mov_b32_e32 v85, v4
	v_mov_b32_e32 v86, v4
	v_mov_b32_e32 v87, v4
	v_mov_b32_e32 v88, v4
	v_mov_b32_e32 v89, v4
	v_mov_b32_e32 v90, v4
	v_mov_b32_e32 v91, v4
	v_mov_b32_e32 v100, v4
	v_mov_b32_e32 v101, v4
	v_mov_b32_e32 v102, v4
	v_mov_b32_e32 v103, v4
	v_mov_b32_e32 v104, v4
	v_mov_b32_e32 v105, v4
	v_mov_b32_e32 v106, v4
	v_mov_b32_e32 v107, v4
	v_mov_b32_e32 v116, v4
	v_mov_b32_e32 v117, v4
	v_mov_b32_e32 v118, v4
	v_mov_b32_e32 v119, v4
	v_mov_b32_e32 v120, v4
	v_mov_b32_e32 v121, v4
	v_mov_b32_e32 v122, v4
	v_mov_b32_e32 v123, v4
	v_mov_b32_e32 v76, v4
	v_mov_b32_e32 v77, v4
	v_mov_b32_e32 v78, v4
	v_mov_b32_e32 v79, v4
	v_mov_b32_e32 v80, v4
	v_mov_b32_e32 v81, v4
	v_mov_b32_e32 v82, v4
	v_mov_b32_e32 v83, v4
	v_mov_b32_e32 v92, v4
	v_mov_b32_e32 v93, v4
	v_mov_b32_e32 v94, v4
	v_mov_b32_e32 v95, v4
	v_mov_b32_e32 v96, v4
	v_mov_b32_e32 v97, v4
	v_mov_b32_e32 v98, v4
	v_mov_b32_e32 v99, v4
	v_mov_b32_e32 v108, v4
	v_mov_b32_e32 v109, v4
	v_mov_b32_e32 v110, v4
	v_mov_b32_e32 v111, v4
	v_mov_b32_e32 v112, v4
	v_mov_b32_e32 v113, v4
	v_mov_b32_e32 v114, v4
	v_mov_b32_e32 v115, v4
	v_mov_b32_e32 v124, v4
	v_mov_b32_e32 v125, v4
	v_mov_b32_e32 v126, v4
	v_mov_b32_e32 v127, v4
	v_mov_b32_e32 v128, v4
	v_mov_b32_e32 v129, v4
	v_mov_b32_e32 v130, v4
	v_mov_b32_e32 v131, v4
	v_readfirstlane_b32 s100, v0
	s_nop 0
	s_cmpk_ge_u32 s100, 0x100
	s_cbranch_scc1 .Lsp_205
	s_setprio 1

.LBB0_365:
	s_add_u32 s31, s28, 0x100
	v_mov_b32_e32 v4, 0
	s_addc_u32 s33, s29, 0
	s_mov_b32 s22, -2
	v_mov_b32_e32 v5, v4
	v_mov_b32_e32 v6, v4
	v_mov_b32_e32 v7, v4
	v_mov_b32_e32 v8, v4
	v_mov_b32_e32 v9, v4
	v_mov_b32_e32 v10, v4
	v_mov_b32_e32 v11, v4
	v_mov_b32_e32 v20, v4
	v_mov_b32_e32 v21, v4
	v_mov_b32_e32 v22, v4
	v_mov_b32_e32 v23, v4
	v_mov_b32_e32 v24, v4
	v_mov_b32_e32 v25, v4
	s_waitcnt lgkmcnt(0)
	v_mov_b32_e32 v26, v4
	v_mov_b32_e32 v27, v4
	v_mov_b32_e32 v36, v4
	v_mov_b32_e32 v37, v4
	v_mov_b32_e32 v38, v4
	v_mov_b32_e32 v39, v4
	v_mov_b32_e32 v40, v4
	v_mov_b32_e32 v41, v4
	v_mov_b32_e32 v42, v4
	v_mov_b32_e32 v43, v4
	v_mov_b32_e32 v52, v4
	v_mov_b32_e32 v53, v4
	v_mov_b32_e32 v54, v4
	v_mov_b32_e32 v55, v4
	v_mov_b32_e32 v56, v4
	v_mov_b32_e32 v57, v4
	v_mov_b32_e32 v58, v4
	v_mov_b32_e32 v59, v4
	v_mov_b32_e32 v12, v4
	v_mov_b32_e32 v13, v4
	v_mov_b32_e32 v14, v4
	v_mov_b32_e32 v15, v4
	v_mov_b32_e32 v16, v4
	v_mov_b32_e32 v17, v4
	v_mov_b32_e32 v18, v4
	v_mov_b32_e32 v19, v4
	v_mov_b32_e32 v28, v4
	v_mov_b32_e32 v29, v4
	v_mov_b32_e32 v30, v4
	v_mov_b32_e32 v31, v4
	v_mov_b32_e32 v32, v4
	v_mov_b32_e32 v33, v4
	v_mov_b32_e32 v34, v4
	v_mov_b32_e32 v35, v4
	v_mov_b32_e32 v44, v4
	v_mov_b32_e32 v45, v4
	v_mov_b32_e32 v46, v4
	v_mov_b32_e32 v47, v4
	v_mov_b32_e32 v48, v4
	v_mov_b32_e32 v49, v4
	v_mov_b32_e32 v50, v4
	v_mov_b32_e32 v51, v4
	v_mov_b32_e32 v60, v4
	v_mov_b32_e32 v61, v4
	v_mov_b32_e32 v62, v4
	v_mov_b32_e32 v63, v4
	v_mov_b32_e32 v64, v4
	v_mov_b32_e32 v65, v4
	v_mov_b32_e32 v66, v4
	v_mov_b32_e32 v67, v4
	v_mov_b32_e32 v68, v4
	v_mov_b32_e32 v69, v4
	v_mov_b32_e32 v70, v4
	v_mov_b32_e32 v71, v4
	v_mov_b32_e32 v72, v4
	v_mov_b32_e32 v73, v4
	v_mov_b32_e32 v74, v4
	v_mov_b32_e32 v75, v4
	v_mov_b32_e32 v84, v4
	v_mov_b32_e32 v85, v4
	v_mov_b32_e32 v86, v4
	v_mov_b32_e32 v87, v4
	v_mov_b32_e32 v88, v4
	v_mov_b32_e32 v89, v4
	v_mov_b32_e32 v90, v4
	v_mov_b32_e32 v91, v4
	v_mov_b32_e32 v100, v4
	v_mov_b32_e32 v101, v4
	v_mov_b32_e32 v102, v4
	v_mov_b32_e32 v103, v4
	v_mov_b32_e32 v104, v4
	v_mov_b32_e32 v105, v4
	v_mov_b32_e32 v106, v4
	v_mov_b32_e32 v107, v4
	v_mov_b32_e32 v116, v4
	v_mov_b32_e32 v117, v4
	v_mov_b32_e32 v118, v4
	v_mov_b32_e32 v119, v4
	v_mov_b32_e32 v120, v4
	v_mov_b32_e32 v121, v4
	v_mov_b32_e32 v122, v4
	v_mov_b32_e32 v123, v4
	v_mov_b32_e32 v76, v4
	v_mov_b32_e32 v77, v4
	v_mov_b32_e32 v78, v4
	v_mov_b32_e32 v79, v4
	v_mov_b32_e32 v80, v4
	v_mov_b32_e32 v81, v4
	v_mov_b32_e32 v82, v4
	v_mov_b32_e32 v83, v4
	v_mov_b32_e32 v92, v4
	v_mov_b32_e32 v93, v4
	v_mov_b32_e32 v94, v4
	v_mov_b32_e32 v95, v4
	v_mov_b32_e32 v96, v4
	v_mov_b32_e32 v97, v4
	v_mov_b32_e32 v98, v4
	v_mov_b32_e32 v99, v4
	v_mov_b32_e32 v108, v4
	v_mov_b32_e32 v109, v4
	v_mov_b32_e32 v110, v4
	v_mov_b32_e32 v111, v4
	v_mov_b32_e32 v112, v4
	v_mov_b32_e32 v113, v4
	v_mov_b32_e32 v114, v4
	v_mov_b32_e32 v115, v4
	v_mov_b32_e32 v124, v4
	v_mov_b32_e32 v125, v4
	v_mov_b32_e32 v126, v4
	v_mov_b32_e32 v127, v4
	v_mov_b32_e32 v128, v4
	v_mov_b32_e32 v129, v4
	v_mov_b32_e32 v130, v4
	v_mov_b32_e32 v131, v4
	v_readfirstlane_b32 s100, v0
	s_nop 0
	s_cmpk_ge_u32 s100, 0x100
	s_cbranch_scc1 .Lsp_366
	s_setprio 1

.LBB0_445:
	s_ashr_i32 s37, s36, 31
	s_lshl_b64 s[16:17], s[36:37], 20
	s_add_u32 s40, s0, s16
	s_addc_u32 s41, s1, s17
	s_and_b64 s[16:17], s[38:39], exec
	s_cselect_b32 s37, s41, s45
	s_cselect_b32 s88, s40, s44
	s_ashr_i32 s27, s26, 31
	s_lshl_b64 s[16:17], s[26:27], 20
	s_add_u32 s42, s3, s16
	s_addc_u32 s43, s31, s17
	s_and_b64 s[16:17], s[38:39], exec
	s_cselect_b32 s27, s43, s29
	s_cselect_b32 s89, s42, s28
	s_add_u32 s44, s44, 0x80080
	s_addc_u32 s45, s45, 0
	s_add_u32 s91, s28, 0x100
	v_mov_b32_e32 v4, 0
	v_mov_b32_e32 v235, 0x42000000
	v_mov_b32_e32 v233, 0x400
	v_mov_b64_e32 v[240:241], 0x1080
	s_addc_u32 s96, s29, 0
	s_mov_b32 vcc_lo, -2
	v_mov_b32_e32 v5, v4
	v_mov_b32_e32 v6, v4
	v_mov_b32_e32 v7, v4
	v_mov_b32_e32 v8, v4
	v_mov_b32_e32 v9, v4
	v_mov_b32_e32 v10, v4
	v_mov_b32_e32 v11, v4
	v_mov_b32_e32 v20, v4
	v_mov_b32_e32 v21, v4
	v_mov_b32_e32 v22, v4
	v_mov_b32_e32 v23, v4
	v_mov_b32_e32 v24, v4
	v_mov_b32_e32 v25, v4
	s_waitcnt lgkmcnt(0)
	v_mov_b32_e32 v26, v4
	v_mov_b32_e32 v27, v4
	v_mov_b32_e32 v36, v4
	v_mov_b32_e32 v37, v4
	v_mov_b32_e32 v38, v4
	v_mov_b32_e32 v39, v4
	v_mov_b32_e32 v40, v4
	v_mov_b32_e32 v41, v4
	v_mov_b32_e32 v42, v4
	v_mov_b32_e32 v43, v4
	v_mov_b32_e32 v52, v4
	v_mov_b32_e32 v53, v4
	v_mov_b32_e32 v54, v4
	v_mov_b32_e32 v55, v4
	v_mov_b32_e32 v56, v4
	v_mov_b32_e32 v57, v4
	v_mov_b32_e32 v58, v4
	v_mov_b32_e32 v59, v4
	v_mov_b32_e32 v12, v4
	v_mov_b32_e32 v13, v4
	v_mov_b32_e32 v14, v4
	v_mov_b32_e32 v15, v4
	v_mov_b32_e32 v16, v4
	v_mov_b32_e32 v17, v4
	v_mov_b32_e32 v18, v4
	v_mov_b32_e32 v19, v4
	v_mov_b32_e32 v28, v4
	v_mov_b32_e32 v29, v4
	v_mov_b32_e32 v30, v4
	v_mov_b32_e32 v31, v4
	v_mov_b32_e32 v32, v4
	v_mov_b32_e32 v33, v4
	v_mov_b32_e32 v34, v4
	v_mov_b32_e32 v35, v4
	v_mov_b32_e32 v44, v4
	v_mov_b32_e32 v45, v4
	v_mov_b32_e32 v46, v4
	v_mov_b32_e32 v47, v4
	v_mov_b32_e32 v48, v4
	v_mov_b32_e32 v49, v4
	v_mov_b32_e32 v50, v4
	v_mov_b32_e32 v51, v4
	v_mov_b32_e32 v60, v4
	v_mov_b32_e32 v61, v4
	v_mov_b32_e32 v62, v4
	v_mov_b32_e32 v63, v4
	v_mov_b32_e32 v64, v4
	v_mov_b32_e32 v65, v4
	v_mov_b32_e32 v66, v4
	v_mov_b32_e32 v67, v4
	v_mov_b32_e32 v68, v4
	v_mov_b32_e32 v69, v4
	v_mov_b32_e32 v70, v4
	v_mov_b32_e32 v71, v4
	v_mov_b32_e32 v72, v4
	v_mov_b32_e32 v73, v4
	v_mov_b32_e32 v74, v4
	v_mov_b32_e32 v75, v4
	v_mov_b32_e32 v84, v4
	v_mov_b32_e32 v85, v4
	v_mov_b32_e32 v86, v4
	v_mov_b32_e32 v87, v4
	v_mov_b32_e32 v88, v4
	v_mov_b32_e32 v89, v4
	v_mov_b32_e32 v90, v4
	v_mov_b32_e32 v91, v4
	v_mov_b32_e32 v100, v4
	v_mov_b32_e32 v101, v4
	v_mov_b32_e32 v102, v4
	v_mov_b32_e32 v103, v4
	v_mov_b32_e32 v104, v4
	v_mov_b32_e32 v105, v4
	v_mov_b32_e32 v106, v4
	v_mov_b32_e32 v107, v4
	v_mov_b32_e32 v116, v4
	v_mov_b32_e32 v117, v4
	v_mov_b32_e32 v118, v4
	v_mov_b32_e32 v119, v4
	v_mov_b32_e32 v120, v4
	v_mov_b32_e32 v121, v4
	v_mov_b32_e32 v122, v4
	v_mov_b32_e32 v123, v4
	v_mov_b32_e32 v76, v4
	v_mov_b32_e32 v77, v4
	v_mov_b32_e32 v78, v4
	v_mov_b32_e32 v79, v4
	v_mov_b32_e32 v80, v4
	v_mov_b32_e32 v81, v4
	v_mov_b32_e32 v82, v4
	v_mov_b32_e32 v83, v4
	v_mov_b32_e32 v92, v4
	v_mov_b32_e32 v93, v4
	v_mov_b32_e32 v94, v4
	v_mov_b32_e32 v95, v4
	v_mov_b32_e32 v96, v4
	v_mov_b32_e32 v97, v4
	v_mov_b32_e32 v98, v4
	v_mov_b32_e32 v99, v4
	v_mov_b32_e32 v108, v4
	v_mov_b32_e32 v109, v4
	v_mov_b32_e32 v110, v4
	v_mov_b32_e32 v111, v4
	v_mov_b32_e32 v112, v4
	v_mov_b32_e32 v113, v4
	v_mov_b32_e32 v114, v4
	v_mov_b32_e32 v115, v4
	v_mov_b32_e32 v124, v4
	v_mov_b32_e32 v125, v4
	v_mov_b32_e32 v126, v4
	v_mov_b32_e32 v127, v4
	v_mov_b32_e32 v128, v4
	v_mov_b32_e32 v129, v4
	v_mov_b32_e32 v130, v4
	v_mov_b32_e32 v131, v4
	v_readfirstlane_b32 s100, v0
	s_nop 0
	s_cmpk_ge_u32 s100, 0x100
	s_cbranch_scc1 .Lsp_446
	s_setprio 1

.LBB0_789:
	s_ashr_i32 s19, s18, 31
	s_lshl_b64 s[10:11], s[18:19], 20
	v_readlane_b32 s16, v252, 15
	s_add_u32 s50, s16, s10
	v_readlane_b32 s10, v252, 16
	s_addc_u32 s51, s10, s11
	s_and_b64 s[10:11], s[46:47], exec
	s_cselect_b32 s19, s51, s73
	s_cselect_b32 s31, s50, s72
	s_ashr_i32 s23, s22, 31
	s_lshl_b64 s[10:11], s[22:23], 20
	s_add_u32 s26, s36, s10
	s_addc_u32 s27, s37, s11
	s_and_b64 s[10:11], s[46:47], exec
	s_cselect_b32 s23, s27, s29
	s_cselect_b32 s33, s26, s28
	s_add_u32 vcc_lo, s72, 0x80080
	s_addc_u32 vcc_hi, s73, 0
	s_add_u32 s48, s28, 0x100
	v_mov_b32_e32 v4, 0
	s_addc_u32 s49, s29, 0
	s_mov_b32 s10, -2
	v_mov_b32_e32 v5, v4
	v_mov_b32_e32 v6, v4
	v_mov_b32_e32 v7, v4
	v_mov_b32_e32 v8, v4
	v_mov_b32_e32 v9, v4
	v_mov_b32_e32 v10, v4
	v_mov_b32_e32 v11, v4
	v_mov_b32_e32 v20, v4
	v_mov_b32_e32 v21, v4
	v_mov_b32_e32 v22, v4
	v_mov_b32_e32 v23, v4
	v_mov_b32_e32 v24, v4
	v_mov_b32_e32 v25, v4
	s_waitcnt lgkmcnt(0)
	v_mov_b32_e32 v26, v4
	v_mov_b32_e32 v27, v4
	v_mov_b32_e32 v36, v4
	v_mov_b32_e32 v37, v4
	v_mov_b32_e32 v38, v4
	v_mov_b32_e32 v39, v4
	v_mov_b32_e32 v40, v4
	v_mov_b32_e32 v41, v4
	v_mov_b32_e32 v42, v4
	v_mov_b32_e32 v43, v4
	v_mov_b32_e32 v52, v4
	v_mov_b32_e32 v53, v4
	v_mov_b32_e32 v54, v4
	v_mov_b32_e32 v55, v4
	v_mov_b32_e32 v56, v4
	v_mov_b32_e32 v57, v4
	v_mov_b32_e32 v58, v4
	v_mov_b32_e32 v59, v4
	v_mov_b32_e32 v12, v4
	v_mov_b32_e32 v13, v4
	v_mov_b32_e32 v14, v4
	v_mov_b32_e32 v15, v4
	v_mov_b32_e32 v16, v4
	v_mov_b32_e32 v17, v4
	v_mov_b32_e32 v18, v4
	v_mov_b32_e32 v19, v4
	v_mov_b32_e32 v28, v4
	v_mov_b32_e32 v29, v4
	v_mov_b32_e32 v30, v4
	v_mov_b32_e32 v31, v4
	v_mov_b32_e32 v32, v4
	v_mov_b32_e32 v33, v4
	v_mov_b32_e32 v34, v4
	v_mov_b32_e32 v35, v4
	v_mov_b32_e32 v44, v4
	v_mov_b32_e32 v45, v4
	v_mov_b32_e32 v46, v4
	v_mov_b32_e32 v47, v4
	v_mov_b32_e32 v48, v4
	v_mov_b32_e32 v49, v4
	v_mov_b32_e32 v50, v4
	v_mov_b32_e32 v51, v4
	v_mov_b32_e32 v60, v4
	v_mov_b32_e32 v61, v4
	v_mov_b32_e32 v62, v4
	v_mov_b32_e32 v63, v4
	v_mov_b32_e32 v64, v4
	v_mov_b32_e32 v65, v4
	v_mov_b32_e32 v66, v4
	v_mov_b32_e32 v67, v4
	v_mov_b32_e32 v68, v4
	v_mov_b32_e32 v69, v4
	v_mov_b32_e32 v70, v4
	v_mov_b32_e32 v71, v4
	v_mov_b32_e32 v72, v4
	v_mov_b32_e32 v73, v4
	v_mov_b32_e32 v74, v4
	v_mov_b32_e32 v75, v4
	v_mov_b32_e32 v84, v4
	v_mov_b32_e32 v85, v4
	v_mov_b32_e32 v86, v4
	v_mov_b32_e32 v87, v4
	v_mov_b32_e32 v88, v4
	v_mov_b32_e32 v89, v4
	v_mov_b32_e32 v90, v4
	v_mov_b32_e32 v91, v4
	v_mov_b32_e32 v100, v4
	v_mov_b32_e32 v101, v4
	v_mov_b32_e32 v102, v4
	v_mov_b32_e32 v103, v4
	v_mov_b32_e32 v104, v4
	v_mov_b32_e32 v105, v4
	v_mov_b32_e32 v106, v4
	v_mov_b32_e32 v107, v4
	v_mov_b32_e32 v116, v4
	v_mov_b32_e32 v117, v4
	v_mov_b32_e32 v118, v4
	v_mov_b32_e32 v119, v4
	v_mov_b32_e32 v120, v4
	v_mov_b32_e32 v121, v4
	v_mov_b32_e32 v122, v4
	v_mov_b32_e32 v123, v4
	v_mov_b32_e32 v76, v4
	v_mov_b32_e32 v77, v4
	v_mov_b32_e32 v78, v4
	v_mov_b32_e32 v79, v4
	v_mov_b32_e32 v80, v4
	v_mov_b32_e32 v81, v4
	v_mov_b32_e32 v82, v4
	v_mov_b32_e32 v83, v4
	v_mov_b32_e32 v92, v4
	v_mov_b32_e32 v93, v4
	v_mov_b32_e32 v94, v4
	v_mov_b32_e32 v95, v4
	v_mov_b32_e32 v96, v4
	v_mov_b32_e32 v97, v4
	v_mov_b32_e32 v98, v4
	v_mov_b32_e32 v99, v4
	v_mov_b32_e32 v108, v4
	v_mov_b32_e32 v109, v4
	v_mov_b32_e32 v110, v4
	v_mov_b32_e32 v111, v4
	v_mov_b32_e32 v112, v4
	v_mov_b32_e32 v113, v4
	v_mov_b32_e32 v114, v4
	v_mov_b32_e32 v115, v4
	v_mov_b32_e32 v124, v4
	v_mov_b32_e32 v125, v4
	v_mov_b32_e32 v126, v4
	v_mov_b32_e32 v127, v4
	v_mov_b32_e32 v128, v4
	v_mov_b32_e32 v129, v4
	v_mov_b32_e32 v130, v4
	v_mov_b32_e32 v131, v4
	v_readfirstlane_b32 s100, v0
	s_nop 0
	s_cmpk_ge_u32 s100, 0x100
	s_cbranch_scc1 .Lsp_790
	s_setprio 1

.LBB0_869:
	s_ashr_i32 s37, s36, 31
	s_lshl_b64 s[16:17], s[36:37], 20
	s_add_u32 s40, s0, s16
	s_addc_u32 s41, s1, s17
	s_and_b64 s[16:17], s[38:39], exec
	s_cselect_b32 s37, s41, s45
	s_cselect_b32 s88, s40, s44
	s_ashr_i32 s27, s26, 31
	s_lshl_b64 s[16:17], s[26:27], 20
	s_add_u32 s42, s3, s16
	s_addc_u32 s43, s31, s17
	s_and_b64 s[16:17], s[38:39], exec
	s_cselect_b32 s27, s43, s29
	s_cselect_b32 s89, s42, s28
	s_add_u32 s44, s44, 0x80080
	s_addc_u32 s45, s45, 0
	s_add_u32 s91, s28, 0x100
	v_mov_b32_e32 v4, 0
	s_addc_u32 s96, s29, 0
	s_mov_b32 vcc_lo, -2
	v_mov_b32_e32 v5, v4
	v_mov_b32_e32 v6, v4
	v_mov_b32_e32 v7, v4
	v_mov_b32_e32 v8, v4
	v_mov_b32_e32 v9, v4
	v_mov_b32_e32 v10, v4
	v_mov_b32_e32 v11, v4
	v_mov_b32_e32 v20, v4
	v_mov_b32_e32 v21, v4
	v_mov_b32_e32 v22, v4
	v_mov_b32_e32 v23, v4
	v_mov_b32_e32 v24, v4
	v_mov_b32_e32 v25, v4
	s_waitcnt lgkmcnt(0)
	v_mov_b32_e32 v26, v4
	v_mov_b32_e32 v27, v4
	v_mov_b32_e32 v36, v4
	v_mov_b32_e32 v37, v4
	v_mov_b32_e32 v38, v4
	v_mov_b32_e32 v39, v4
	v_mov_b32_e32 v40, v4
	v_mov_b32_e32 v41, v4
	v_mov_b32_e32 v42, v4
	v_mov_b32_e32 v43, v4
	v_mov_b32_e32 v52, v4
	v_mov_b32_e32 v53, v4
	v_mov_b32_e32 v54, v4
	v_mov_b32_e32 v55, v4
	v_mov_b32_e32 v56, v4
	v_mov_b32_e32 v57, v4
	v_mov_b32_e32 v58, v4
	v_mov_b32_e32 v59, v4
	v_mov_b32_e32 v12, v4
	v_mov_b32_e32 v13, v4
	v_mov_b32_e32 v14, v4
	v_mov_b32_e32 v15, v4
	v_mov_b32_e32 v16, v4
	v_mov_b32_e32 v17, v4
	v_mov_b32_e32 v18, v4
	v_mov_b32_e32 v19, v4
	v_mov_b32_e32 v28, v4
	v_mov_b32_e32 v29, v4
	v_mov_b32_e32 v30, v4
	v_mov_b32_e32 v31, v4
	v_mov_b32_e32 v32, v4
	v_mov_b32_e32 v33, v4
	v_mov_b32_e32 v34, v4
	v_mov_b32_e32 v35, v4
	v_mov_b32_e32 v44, v4
	v_mov_b32_e32 v45, v4
	v_mov_b32_e32 v46, v4
	v_mov_b32_e32 v47, v4
	v_mov_b32_e32 v48, v4
	v_mov_b32_e32 v49, v4
	v_mov_b32_e32 v50, v4
	v_mov_b32_e32 v51, v4
	v_mov_b32_e32 v60, v4
	v_mov_b32_e32 v61, v4
	v_mov_b32_e32 v62, v4
	v_mov_b32_e32 v63, v4
	v_mov_b32_e32 v64, v4
	v_mov_b32_e32 v65, v4
	v_mov_b32_e32 v66, v4
	v_mov_b32_e32 v67, v4
	v_mov_b32_e32 v68, v4
	v_mov_b32_e32 v69, v4
	v_mov_b32_e32 v70, v4
	v_mov_b32_e32 v71, v4
	v_mov_b32_e32 v72, v4
	v_mov_b32_e32 v73, v4
	v_mov_b32_e32 v74, v4
	v_mov_b32_e32 v75, v4
	v_mov_b32_e32 v84, v4
	v_mov_b32_e32 v85, v4
	v_mov_b32_e32 v86, v4
	v_mov_b32_e32 v87, v4
	v_mov_b32_e32 v88, v4
	v_mov_b32_e32 v89, v4
	v_mov_b32_e32 v90, v4
	v_mov_b32_e32 v91, v4
	v_mov_b32_e32 v100, v4
	v_mov_b32_e32 v101, v4
	v_mov_b32_e32 v102, v4
	v_mov_b32_e32 v103, v4
	v_mov_b32_e32 v104, v4
	v_mov_b32_e32 v105, v4
	v_mov_b32_e32 v106, v4
	v_mov_b32_e32 v107, v4
	v_mov_b32_e32 v116, v4
	v_mov_b32_e32 v117, v4
	v_mov_b32_e32 v118, v4
	v_mov_b32_e32 v119, v4
	v_mov_b32_e32 v120, v4
	v_mov_b32_e32 v121, v4
	v_mov_b32_e32 v122, v4
	v_mov_b32_e32 v123, v4
	v_mov_b32_e32 v76, v4
	v_mov_b32_e32 v77, v4
	v_mov_b32_e32 v78, v4
	v_mov_b32_e32 v79, v4
	v_mov_b32_e32 v80, v4
	v_mov_b32_e32 v81, v4
	v_mov_b32_e32 v82, v4
	v_mov_b32_e32 v83, v4
	v_mov_b32_e32 v92, v4
	v_mov_b32_e32 v93, v4
	v_mov_b32_e32 v94, v4
	v_mov_b32_e32 v95, v4
	v_mov_b32_e32 v96, v4
	v_mov_b32_e32 v97, v4
	v_mov_b32_e32 v98, v4
	v_mov_b32_e32 v99, v4
	v_mov_b32_e32 v108, v4
	v_mov_b32_e32 v109, v4
	v_mov_b32_e32 v110, v4
	v_mov_b32_e32 v111, v4
	v_mov_b32_e32 v112, v4
	v_mov_b32_e32 v113, v4
	v_mov_b32_e32 v114, v4
	v_mov_b32_e32 v115, v4
	v_mov_b32_e32 v124, v4
	v_mov_b32_e32 v125, v4
	v_mov_b32_e32 v126, v4
	v_mov_b32_e32 v127, v4
	v_mov_b32_e32 v128, v4
	v_mov_b32_e32 v129, v4
	v_mov_b32_e32 v130, v4
	v_mov_b32_e32 v131, v4
	v_readfirstlane_b32 s100, v0
	s_nop 0
	s_cmpk_ge_u32 s100, 0x100
	s_cbranch_scc1 .Lsp_870
	s_setprio 1

.LBB0_1034:
	s_add_u32 vcc_lo, s28, 0x100
	v_mov_b32_e32 v4, 0
	s_addc_u32 vcc_hi, s29, 0
	s_mov_b32 s48, -2
	v_mov_b32_e32 v5, v4
	v_mov_b32_e32 v6, v4
	v_mov_b32_e32 v7, v4
	v_mov_b32_e32 v8, v4
	v_mov_b32_e32 v9, v4
	v_mov_b32_e32 v10, v4
	v_mov_b32_e32 v11, v4
	v_mov_b32_e32 v20, v4
	v_mov_b32_e32 v21, v4
	v_mov_b32_e32 v22, v4
	v_mov_b32_e32 v23, v4
	v_mov_b32_e32 v24, v4
	v_mov_b32_e32 v25, v4
	s_waitcnt lgkmcnt(0)
	v_mov_b32_e32 v26, v4
	v_mov_b32_e32 v27, v4
	v_mov_b32_e32 v36, v4
	v_mov_b32_e32 v37, v4
	v_mov_b32_e32 v38, v4
	v_mov_b32_e32 v39, v4
	v_mov_b32_e32 v40, v4
	v_mov_b32_e32 v41, v4
	v_mov_b32_e32 v42, v4
	v_mov_b32_e32 v43, v4
	v_mov_b32_e32 v52, v4
	v_mov_b32_e32 v53, v4
	v_mov_b32_e32 v54, v4
	v_mov_b32_e32 v55, v4
	v_mov_b32_e32 v56, v4
	v_mov_b32_e32 v57, v4
	v_mov_b32_e32 v58, v4
	v_mov_b32_e32 v59, v4
	v_mov_b32_e32 v12, v4
	v_mov_b32_e32 v13, v4
	v_mov_b32_e32 v14, v4
	v_mov_b32_e32 v15, v4
	v_mov_b32_e32 v16, v4
	v_mov_b32_e32 v17, v4
	v_mov_b32_e32 v18, v4
	v_mov_b32_e32 v19, v4
	v_mov_b32_e32 v28, v4
	v_mov_b32_e32 v29, v4
	v_mov_b32_e32 v30, v4
	v_mov_b32_e32 v31, v4
	v_mov_b32_e32 v32, v4
	v_mov_b32_e32 v33, v4
	v_mov_b32_e32 v34, v4
	v_mov_b32_e32 v35, v4
	v_mov_b32_e32 v44, v4
	v_mov_b32_e32 v45, v4
	v_mov_b32_e32 v46, v4
	v_mov_b32_e32 v47, v4
	v_mov_b32_e32 v48, v4
	v_mov_b32_e32 v49, v4
	v_mov_b32_e32 v50, v4
	v_mov_b32_e32 v51, v4
	v_mov_b32_e32 v60, v4
	v_mov_b32_e32 v61, v4
	v_mov_b32_e32 v62, v4
	v_mov_b32_e32 v63, v4
	v_mov_b32_e32 v64, v4
	v_mov_b32_e32 v65, v4
	v_mov_b32_e32 v66, v4
	v_mov_b32_e32 v67, v4
	v_mov_b32_e32 v68, v4
	v_mov_b32_e32 v69, v4
	v_mov_b32_e32 v70, v4
	v_mov_b32_e32 v71, v4
	v_mov_b32_e32 v72, v4
	v_mov_b32_e32 v73, v4
	v_mov_b32_e32 v74, v4
	v_mov_b32_e32 v75, v4
	v_mov_b32_e32 v84, v4
	v_mov_b32_e32 v85, v4
	v_mov_b32_e32 v86, v4
	v_mov_b32_e32 v87, v4
	v_mov_b32_e32 v88, v4
	v_mov_b32_e32 v89, v4
	v_mov_b32_e32 v90, v4
	v_mov_b32_e32 v91, v4
	v_mov_b32_e32 v100, v4
	v_mov_b32_e32 v101, v4
	v_mov_b32_e32 v102, v4
	v_mov_b32_e32 v103, v4
	v_mov_b32_e32 v104, v4
	v_mov_b32_e32 v105, v4
	v_mov_b32_e32 v106, v4
	v_mov_b32_e32 v107, v4
	v_mov_b32_e32 v116, v4
	v_mov_b32_e32 v117, v4
	v_mov_b32_e32 v118, v4
	v_mov_b32_e32 v119, v4
	v_mov_b32_e32 v120, v4
	v_mov_b32_e32 v121, v4
	v_mov_b32_e32 v122, v4
	v_mov_b32_e32 v123, v4
	v_mov_b32_e32 v76, v4
	v_mov_b32_e32 v77, v4
	v_mov_b32_e32 v78, v4
	v_mov_b32_e32 v79, v4
	v_mov_b32_e32 v80, v4
	v_mov_b32_e32 v81, v4
	v_mov_b32_e32 v82, v4
	v_mov_b32_e32 v83, v4
	v_mov_b32_e32 v92, v4
	v_mov_b32_e32 v93, v4
	v_mov_b32_e32 v94, v4
	v_mov_b32_e32 v95, v4
	v_mov_b32_e32 v96, v4
	v_mov_b32_e32 v97, v4
	v_mov_b32_e32 v98, v4
	v_mov_b32_e32 v99, v4
	v_mov_b32_e32 v108, v4
	v_mov_b32_e32 v109, v4
	v_mov_b32_e32 v110, v4
	v_mov_b32_e32 v111, v4
	v_mov_b32_e32 v112, v4
	v_mov_b32_e32 v113, v4
	v_mov_b32_e32 v114, v4
	v_mov_b32_e32 v115, v4
	v_mov_b32_e32 v124, v4
	v_mov_b32_e32 v125, v4
	v_mov_b32_e32 v126, v4
	v_mov_b32_e32 v127, v4
	v_mov_b32_e32 v128, v4
	v_mov_b32_e32 v129, v4
	v_mov_b32_e32 v130, v4
	v_mov_b32_e32 v131, v4
	v_readfirstlane_b32 s100, v0
	s_nop 0
	s_cmpk_ge_u32 s100, 0x100
	s_cbranch_scc1 .Lsp_1035
	s_setprio 1
